# NOMAX prompt-diff main loop: the three LDS-DMA pieces of each step moved from the QK-PV boundary into PV MFMA gaps (scalar address sums, no m0 save/restore)
# speedup vs baseline: 1.0094x; 1.0094x over previous
; #define TWAIT_BAR(N) asm volatile("s_waitcnt vmcnt(" #N ") lgkmcnt(0)\n\ts_barrier" ::: "memory")
; #define RESC() do { if constexpr (!NOMAX) if (resc) { asm volatile("s_waitcnt lgkmcnt(0)" ::: "memory"); \
;         _Pragma("unroll") for (int d_ = 0; d_ < 2; ++d_) _Pragma("unroll") for (int r = 0; r < 16; ++r) o[d_][r] *= wsf[crow(r, hi)]; } } while (0)
; #define ROT() do { sl_prev = sl_cur; sl_cur = sl_next; sl_next = (sl_next == 2 * SLOTB) ? 0 : sl_next + SLOTB; } while (0)
; #define RESC() do { if constexpr (!NOMAX) if (resc) { asm volatile("s_waitcnt lgkmcnt(0)" ::: "memory"); \
;         _Pragma("unroll") for (int d_ = 0; d_ < 4; ++d_) _Pragma("unroll") for (int r = 0; r < 16; ++r) o[d_][r] *= wsf[crow(r, hi)]; } } while (0)
; #define ROT() do { sl_prev = sl_cur; sl_cur = sl_next; sl_next = (sl_next == 2) ? 0 : sl_next + 1; } while (0)
; #define RESC() do { if (resc) { asm volatile("s_waitcnt lgkmcnt(0)" ::: "memory"); \
;         _Pragma("unroll") for (int d_ = 0; d_ < 4; ++d_) _Pragma("unroll") for (int r = 0; r < 16; ++r) o[d_][r] *= wsf[crow(r, hi)]; } } while (0)
; template <bool NOMAX>
; __device__ __forceinline__ void diff_unit(const AttnCtx& C, int u, LAS unsigned char* lds) {
;     ...
;     int kk = 1;
;     for (; kk + 7 < n; kk += 2) {
;         STEP(pB0, pB1, pA0, pA1, kk, true, true, true, false);     TWAIT_BAR(3); RESC(); ROT();
;         STEP(pA0, pA1, pB0, pB1, kk + 1, true, true, true, false); TWAIT_BAR(3); RESC(); ROT();
.LBB0_463:
	s_mov_b32 s8, s60
	s_mov_b32 s9, s16
	s_mov_b32 s10, s59
	ds_read_b128 v[4:7], v219 offset:1024
	v_lshl_add_u32 v207, s11, 14, v214
	v_add_f32_e32 v2, v100, v101
	v_add_f32_e32 v2, v102, v2
	v_add_f32_e32 v2, v103, v2
	v_add_f32_e32 v2, v104, v2
	v_add_f32_e32 v2, v105, v2
	v_cvt_pk_bf16_f32 v160, v100, v101
	v_cvt_pk_bf16_f32 v161, v102, v103
	s_waitcnt lgkmcnt(1)
	v_mfma_f32_32x32x16_bf16 v[132:147], v[192:195], v[116:119], 0
	v_mfma_f32_32x32x16_bf16 v[116:131], v[184:187], v[116:119], 0
	v_add_f32_e32 v2, v106, v2
	v_add_f32_e32 v2, v107, v2
	v_add_f32_e32 v2, v108, v2
	v_add_f32_e32 v2, v109, v2
	v_cvt_pk_bf16_f32 v162, v104, v105
	v_cvt_pk_bf16_f32 v163, v106, v107
	ds_read_b128 v[10:13], v219 offset:2048
	ds_read_b64_tr_b16 v[14:15], v207 offset:24576
	ds_read_b64_tr_b16 v[16:17], v207 offset:25088
	v_add_f32_e32 v2, v110, v2
	v_add_f32_e32 v2, v111, v2
	v_add_f32_e32 v2, v112, v2
	v_add_f32_e32 v2, v113, v2
	v_cvt_pk_bf16_f32 v156, v108, v109
	v_cvt_pk_bf16_f32 v157, v110, v111
	s_waitcnt lgkmcnt(3)
	v_mfma_f32_32x32x16_bf16 v[132:147], v[188:191], v[4:7], v[132:147]
	v_mfma_f32_32x32x16_bf16 v[116:131], v[180:183], v[4:7], v[116:131]
	v_add_f32_e32 v2, v114, v2
	v_add_f32_e32 v2, v115, v2
	v_add_f32_e32 v2, v84, v2
	v_add_f32_e32 v2, v85, v2
	v_cvt_pk_bf16_f32 v158, v112, v113
	v_cvt_pk_bf16_f32 v159, v114, v115
	ds_read_b128 v[4:7], v219 offset:3072
	ds_read_b64_tr_b16 v[100:101], v207 offset:28672
	ds_read_b64_tr_b16 v[102:103], v207 offset:29184
	v_add_f32_e32 v2, v86, v2
	v_add_f32_e32 v2, v87, v2
	v_add_f32_e32 v2, v88, v2
	v_add_f32_e32 v2, v89, v2
	v_cvt_pk_bf16_f32 v152, v84, v85
	v_cvt_pk_bf16_f32 v153, v86, v87
	s_waitcnt lgkmcnt(5)
	v_mfma_f32_32x32x16_bf16 v[132:147], v[176:179], v[10:13], v[132:147]
	v_mfma_f32_32x32x16_bf16 v[116:131], v[172:175], v[10:13], v[116:131]
	v_add_f32_e32 v2, v90, v2
	v_add_f32_e32 v2, v91, v2
	v_add_f32_e32 v2, v92, v2
	v_add_f32_e32 v2, v93, v2
	v_cvt_pk_bf16_f32 v154, v88, v89
	v_cvt_pk_bf16_f32 v155, v90, v91
	ds_read_b64_tr_b16 v[84:85], v207 offset:25600
	ds_read_b64_tr_b16 v[86:87], v207 offset:26112
	v_add_f32_e32 v2, v94, v2
	v_add_f32_e32 v2, v95, v2
	v_add_f32_e32 v2, v96, v2
	v_add_f32_e32 v2, v97, v2
	v_cvt_pk_bf16_f32 v148, v92, v93
	v_cvt_pk_bf16_f32 v149, v94, v95
	s_waitcnt lgkmcnt(4)
	v_mfma_f32_32x32x16_bf16 v[132:147], v[168:171], v[4:7], v[132:147]
	v_mfma_f32_32x32x16_bf16 v[116:131], v[164:167], v[4:7], v[116:131]
	v_add_f32_e32 v2, v98, v2
	v_add_f32_e32 v2, v99, v2
	v_add_f32_e32 v2, 0, v2
	v_cvt_pk_bf16_f32 v150, v96, v97
	v_cvt_pk_bf16_f32 v151, v98, v99
	v_lshl_add_u64 v[12:13], v[204:205], 0, s[6:7]
	v_lshl_add_u64 v[10:11], v[8:9], 0, s[6:7]
	v_add_f32_e32 v2, v225, v2
	ds_read_b64_tr_b16 v[4:5], v207 offset:29696
	ds_read_b64_tr_b16 v[6:7], v207 offset:30208
	v_mfma_f32_32x32x16_bf16 v[68:83], v[160:163], v[14:17], v[68:83]
	v_exp_f32_e32 v132, v132
	v_exp_f32_e32 v133, v133
	ds_read_b64_tr_b16 v[14:15], v207 offset:26624
	ds_read_b64_tr_b16 v[16:17], v207 offset:27136
	s_waitcnt lgkmcnt(6)
	v_mfma_f32_32x32x16_bf16 v[52:67], v[160:163], v[100:103], v[52:67]
	v_exp_f32_e32 v134, v134
	v_exp_f32_e32 v135, v135
	s_add_u32 s98, s6, s28
	s_addc_u32 s99, s7, s29
	v_lshl_add_u64 v[254:255], v[204:205], 0, s[98:99]
	s_lshl_b32 s100, s59, 13
	s_add_i32 s100, s100, s49
	s_mov_b32 m0, s100
	s_nop 0
	global_load_lds_dwordx4 v[254:255], off
	ds_read_b64_tr_b16 v[88:89], v207 offset:30720
	ds_read_b64_tr_b16 v[90:91], v207 offset:31232
	s_waitcnt lgkmcnt(6)
	v_mfma_f32_32x32x16_bf16 v[68:83], v[156:159], v[84:87], v[68:83]
	v_exp_f32_e32 v136, v136
	v_exp_f32_e32 v137, v137
	ds_read_b64_tr_b16 v[84:85], v207 offset:27648
	ds_read_b64_tr_b16 v[86:87], v207 offset:28160
	s_waitcnt lgkmcnt(6)
	v_mfma_f32_32x32x16_bf16 v[52:67], v[156:159], v[4:7], v[52:67]
	v_exp_f32_e32 v138, v138
	v_exp_f32_e32 v139, v139
	ds_read_b64_tr_b16 v[4:5], v207 offset:31744
	ds_read_b64_tr_b16 v[6:7], v207 offset:32256
	s_waitcnt lgkmcnt(6)
	v_mfma_f32_32x32x16_bf16 v[68:83], v[152:155], v[14:17], v[68:83]
	v_exp_f32_e32 v140, v140
	v_exp_f32_e32 v141, v141
	s_add_u32 s98, s6, s30
	s_addc_u32 s99, s7, s31
	v_lshl_add_u64 v[254:255], v[8:9], 0, s[98:99]
	s_lshl_b32 s100, s60, 14
	s_add_i32 s100, s100, s58
	s_mov_b32 m0, s100
	s_nop 0
	global_load_lds_dwordx4 v[254:255], off
	ds_read_b64_tr_b16 v[14:15], v207 offset:32768
	ds_read_b64_tr_b16 v[16:17], v207 offset:33280
	s_waitcnt lgkmcnt(6)
	v_mfma_f32_32x32x16_bf16 v[52:67], v[152:155], v[88:91], v[52:67]
	v_exp_f32_e32 v142, v142
	v_exp_f32_e32 v143, v143
	ds_read_b64_tr_b16 v[88:89], v207 offset:36864
	ds_read_b64_tr_b16 v[90:91], v207 offset:37376
	s_waitcnt lgkmcnt(6)
	v_mfma_f32_32x32x16_bf16 v[68:83], v[148:151], v[84:87], v[68:83]
	v_exp_f32_e32 v144, v144
	v_exp_f32_e32 v145, v145
	ds_read_b64_tr_b16 v[84:85], v207 offset:33792
	ds_read_b64_tr_b16 v[86:87], v207 offset:34304
	s_waitcnt lgkmcnt(6)
	v_mfma_f32_32x32x16_bf16 v[52:67], v[148:151], v[4:7], v[52:67]
	v_exp_f32_e32 v146, v146
	v_exp_f32_e32 v147, v147
	ds_read_b64_tr_b16 v[92:93], v207 offset:37888
	ds_read_b64_tr_b16 v[94:95], v207 offset:38400
	s_lshl_b32 s11, s60, 13
	v_add_u32_e32 v4, s11, v222
	ds_read_b128 v[96:99], v4
	ds_read_b128 v[164:167], v4 offset:512
	s_waitcnt lgkmcnt(8)
	v_mfma_f32_32x32x16_bf16 v[36:51], v[160:163], v[14:17], v[36:51]
	v_exp_f32_e32 v116, v116
	v_exp_f32_e32 v117, v117
	ds_read_b64_tr_b16 v[14:15], v207 offset:34816
	ds_read_b64_tr_b16 v[16:17], v207 offset:35328
	ds_read_b128 v[168:171], v4 offset:2048
	ds_read_b128 v[172:175], v4 offset:2560
	s_waitcnt lgkmcnt(10)
; #define TWAIT_BAR(N) asm volatile("s_waitcnt vmcnt(" #N ") lgkmcnt(0)\n\ts_barrier" ::: "memory")
; #define RESC() do { if constexpr (!NOMAX) if (resc) { asm volatile("s_waitcnt lgkmcnt(0)" ::: "memory"); \
;         _Pragma("unroll") for (int d_ = 0; d_ < 2; ++d_) _Pragma("unroll") for (int r = 0; r < 16; ++r) o[d_][r] *= wsf[crow(r, hi)]; } } while (0)
; #define ROT() do { sl_prev = sl_cur; sl_cur = sl_next; sl_next = (sl_next == 2 * SLOTB) ? 0 : sl_next + SLOTB; } while (0)
; #define RESC() do { if constexpr (!NOMAX) if (resc) { asm volatile("s_waitcnt lgkmcnt(0)" ::: "memory"); \
;         _Pragma("unroll") for (int d_ = 0; d_ < 4; ++d_) _Pragma("unroll") for (int r = 0; r < 16; ++r) o[d_][r] *= wsf[crow(r, hi)]; } } while (0)
; #define ROT() do { sl_prev = sl_cur; sl_cur = sl_next; sl_next = (sl_next == 2) ? 0 : sl_next + 1; } while (0)
; #define RESC() do { if (resc) { asm volatile("s_waitcnt lgkmcnt(0)" ::: "memory"); \
;         _Pragma("unroll") for (int d_ = 0; d_ < 4; ++d_) _Pragma("unroll") for (int r = 0; r < 16; ++r) o[d_][r] *= wsf[crow(r, hi)]; } } while (0)
; template <bool NOMAX>
; __device__ __forceinline__ void diff_unit(const AttnCtx& C, int u, LAS unsigned char* lds) {
;     ...
;     int kk = 1;
;     for (; kk + 7 < n; kk += 2) {
;         STEP(pB0, pB1, pA0, pA1, kk, true, true, true, false);     TWAIT_BAR(3); RESC(); ROT();
;         STEP(pA0, pA1, pB0, pB1, kk + 1, true, true, true, false); TWAIT_BAR(3); RESC(); ROT();
	v_mfma_f32_32x32x16_bf16 v[20:35], v[160:163], v[88:91], v[20:35]
	v_exp_f32_e32 v118, v118
	v_exp_f32_e32 v119, v119
	ds_read_b64_tr_b16 v[88:89], v207 offset:38912
	ds_read_b64_tr_b16 v[90:91], v207 offset:39424
	ds_read_b128 v[176:179], v4 offset:4096
	ds_read_b128 v[180:183], v4 offset:4608
	s_waitcnt lgkmcnt(12)
	v_mfma_f32_32x32x16_bf16 v[36:51], v[156:159], v[84:87], v[36:51]
	v_exp_f32_e32 v120, v120
	v_exp_f32_e32 v121, v121
	ds_read_b64_tr_b16 v[84:85], v207 offset:35840
	ds_read_b64_tr_b16 v[86:87], v207 offset:36352
	ds_read_b128 v[184:187], v4 offset:6144
	ds_read_b128 v[4:7], v4 offset:6656
	s_waitcnt lgkmcnt(14)
	v_mfma_f32_32x32x16_bf16 v[20:35], v[156:159], v[92:95], v[20:35]
	v_exp_f32_e32 v122, v122
	v_exp_f32_e32 v123, v123
	ds_read_b64_tr_b16 v[92:93], v207 offset:39936
	ds_read_b64_tr_b16 v[94:95], v207 offset:40448
	s_waitcnt lgkmcnt(12)
	v_mfma_f32_32x32x16_bf16 v[36:51], v[152:155], v[14:17], v[36:51]
	v_exp_f32_e32 v124, v124
	v_exp_f32_e32 v125, v125
	ds_read_b128 v[14:17], v219
	s_waitcnt lgkmcnt(9)
	v_mfma_f32_32x32x16_bf16 v[20:35], v[152:155], v[88:91], v[20:35]
	v_exp_f32_e32 v126, v126
	v_exp_f32_e32 v127, v127
	s_add_u32 s98, s6, s34
	s_addc_u32 s99, s7, s35
	v_lshl_add_u64 v[254:255], v[8:9], 0, s[98:99]
	s_lshl_b32 s100, s60, 14
	s_add_i32 s100, s100, s58
	s_addk_i32 s100, 0x2000
	s_mov_b32 m0, s100
	s_nop 0
	global_load_lds_dwordx4 v[254:255], off
	s_waitcnt lgkmcnt(5)
	v_mfma_f32_32x32x16_bf16 v[36:51], v[148:151], v[84:87], v[36:51]
	v_exp_f32_e32 v128, v128
	v_exp_f32_e32 v129, v129
	s_waitcnt lgkmcnt(1)
	v_mfma_f32_32x32x16_bf16 v[20:35], v[148:151], v[92:95], v[20:35]
	v_exp_f32_e32 v130, v130
	v_exp_f32_e32 v131, v131
	s_waitcnt vmcnt(3) lgkmcnt(0)
	s_barrier
	s_add_i32 s16, s60, 1
	s_cmp_lg_u32 s60, 2
	s_cselect_b32 s59, s16, 0
	ds_read_b128 v[188:191], v219 offset:1024
	v_lshl_add_u32 v207, s10, 14, v214
	s_waitcnt lgkmcnt(1)
	v_mfma_f32_32x32x16_bf16 v[100:115], v[96:99], v[14:17], 0
	v_add_f32_e32 v84, v132, v133
	v_add_f32_e32 v84, v134, v84
	v_add_f32_e32 v84, v135, v84
	v_add_f32_e32 v84, v136, v84
	v_add_f32_e32 v84, v137, v84
	v_cvt_pk_bf16_f32 v160, v132, v133
	v_cvt_pk_bf16_f32 v161, v134, v135
	s_nop 0
	v_add_f32_e32 v84, v138, v84
	v_add_f32_e32 v84, v139, v84
	v_add_f32_e32 v84, v140, v84
	v_add_f32_e32 v148, v141, v84
	v_mfma_f32_32x32x16_bf16 v[84:99], v[164:167], v[14:17], 0
	v_cvt_pk_bf16_f32 v162, v136, v137
	v_cvt_pk_bf16_f32 v163, v138, v139
	ds_read_b128 v[14:17], v219 offset:2048
	ds_read_b64_tr_b16 v[132:133], v207 offset:24576
	ds_read_b64_tr_b16 v[134:135], v207 offset:25088
	s_waitcnt lgkmcnt(3)
	v_mfma_f32_32x32x16_bf16 v[100:115], v[168:171], v[188:191], v[100:115]
	v_add_f32_e32 v136, v142, v148
	v_add_f32_e32 v136, v143, v136
	v_add_f32_e32 v136, v144, v136
	v_add_f32_e32 v136, v145, v136
	v_cvt_pk_bf16_f32 v156, v140, v141
	v_cvt_pk_bf16_f32 v157, v142, v143
	v_mfma_f32_32x32x16_bf16 v[84:99], v[172:175], v[188:191], v[84:99]
	v_add_f32_e32 v136, v146, v136
	v_add_f32_e32 v136, v147, v136
	v_add_f32_e32 v136, v116, v136
	v_add_f32_e32 v148, v117, v136
	v_cvt_pk_bf16_f32 v158, v144, v145
	v_cvt_pk_bf16_f32 v159, v146, v147
	ds_read_b128 v[136:139], v219 offset:3072
	ds_read_b64_tr_b16 v[140:141], v207 offset:28672
	ds_read_b64_tr_b16 v[142:143], v207 offset:29184
	s_waitcnt lgkmcnt(5)
	v_mfma_f32_32x32x16_bf16 v[100:115], v[176:179], v[14:17], v[100:115]
	v_add_f32_e32 v144, v118, v148
	v_add_f32_e32 v144, v119, v144
	v_add_f32_e32 v144, v120, v144
	v_add_f32_e32 v144, v121, v144
	v_cvt_pk_bf16_f32 v152, v116, v117
	v_cvt_pk_bf16_f32 v153, v118, v119
	v_mfma_f32_32x32x16_bf16 v[84:99], v[180:183], v[14:17], v[84:99]
	v_add_f32_e32 v14, v122, v144
	v_add_f32_e32 v14, v123, v14
	v_add_f32_e32 v14, v124, v14
	v_add_f32_e32 v116, v125, v14
	v_cvt_pk_bf16_f32 v154, v120, v121
	v_cvt_pk_bf16_f32 v155, v122, v123
	ds_read_b64_tr_b16 v[14:15], v207 offset:25600
	ds_read_b64_tr_b16 v[16:17], v207 offset:26112
	s_waitcnt lgkmcnt(4)
	v_mfma_f32_32x32x16_bf16 v[100:115], v[184:187], v[136:139], v[100:115]
	v_add_f32_e32 v116, v126, v116
	v_add_f32_e32 v116, v127, v116
	v_add_f32_e32 v116, v128, v116
	v_add_f32_e32 v116, v129, v116
	v_cvt_pk_bf16_f32 v148, v124, v125
	v_cvt_pk_bf16_f32 v149, v126, v127
	v_mfma_f32_32x32x16_bf16 v[84:99], v[4:7], v[136:139], v[84:99]
	v_add_f32_e32 v4, v130, v116
	v_add_f32_e32 v4, v131, v4
	v_add_f32_e32 v4, 0, v4
	v_cvt_pk_bf16_f32 v150, v128, v129
	v_cvt_pk_bf16_f32 v151, v130, v131
	v_add_f32_e32 v225, v2, v4
	ds_read_b64_tr_b16 v[4:5], v207 offset:29696
	ds_read_b64_tr_b16 v[6:7], v207 offset:30208
	v_mfma_f32_32x32x16_bf16 v[68:83], v[160:163], v[132:135], v[68:83]
	v_exp_f32_e32 v100, v100
	v_exp_f32_e32 v101, v101
	ds_read_b64_tr_b16 v[10:11], v207 offset:26624
	ds_read_b64_tr_b16 v[12:13], v207 offset:27136
	s_waitcnt lgkmcnt(6)
; #define TWAIT_BAR(N) asm volatile("s_waitcnt vmcnt(" #N ") lgkmcnt(0)\n\ts_barrier" ::: "memory")
; #define RESC() do { if constexpr (!NOMAX) if (resc) { asm volatile("s_waitcnt lgkmcnt(0)" ::: "memory"); \
;         _Pragma("unroll") for (int d_ = 0; d_ < 2; ++d_) _Pragma("unroll") for (int r = 0; r < 16; ++r) o[d_][r] *= wsf[crow(r, hi)]; } } while (0)
; #define ROT() do { sl_prev = sl_cur; sl_cur = sl_next; sl_next = (sl_next == 2 * SLOTB) ? 0 : sl_next + SLOTB; } while (0)
; #define RESC() do { if constexpr (!NOMAX) if (resc) { asm volatile("s_waitcnt lgkmcnt(0)" ::: "memory"); \
;         _Pragma("unroll") for (int d_ = 0; d_ < 4; ++d_) _Pragma("unroll") for (int r = 0; r < 16; ++r) o[d_][r] *= wsf[crow(r, hi)]; } } while (0)
; #define ROT() do { sl_prev = sl_cur; sl_cur = sl_next; sl_next = (sl_next == 2) ? 0 : sl_next + 1; } while (0)
; #define RESC() do { if (resc) { asm volatile("s_waitcnt lgkmcnt(0)" ::: "memory"); \
;         _Pragma("unroll") for (int d_ = 0; d_ < 4; ++d_) _Pragma("unroll") for (int r = 0; r < 16; ++r) o[d_][r] *= wsf[crow(r, hi)]; } } while (0)
; template <bool NOMAX>
; __device__ __forceinline__ void diff_unit(const AttnCtx& C, int u, LAS unsigned char* lds) {
;     ...
;     int kk = 1;
;     for (; kk + 7 < n; kk += 2) {
;         STEP(pB0, pB1, pA0, pA1, kk, true, true, true, false);     TWAIT_BAR(3); RESC(); ROT();
;         STEP(pA0, pA1, pB0, pB1, kk + 1, true, true, true, false); TWAIT_BAR(3); RESC(); ROT();
	v_mfma_f32_32x32x16_bf16 v[52:67], v[160:163], v[140:143], v[52:67]
	v_exp_f32_e32 v102, v102
	v_exp_f32_e32 v103, v103
	s_add_u32 s98, s6, s36
	s_addc_u32 s99, s7, s37
	v_lshl_add_u64 v[254:255], v[204:205], 0, s[98:99]
	s_lshl_b32 s100, s60, 13
	s_add_i32 s100, s100, s49
	s_mov_b32 m0, s100
	s_nop 0
	global_load_lds_dwordx4 v[254:255], off
	ds_read_b64_tr_b16 v[116:117], v207 offset:30720
	ds_read_b64_tr_b16 v[118:119], v207 offset:31232
	s_waitcnt lgkmcnt(6)
	v_mfma_f32_32x32x16_bf16 v[68:83], v[156:159], v[14:17], v[68:83]
	v_exp_f32_e32 v104, v104
	v_exp_f32_e32 v105, v105
	ds_read_b64_tr_b16 v[14:15], v207 offset:27648
	ds_read_b64_tr_b16 v[16:17], v207 offset:28160
	s_waitcnt lgkmcnt(6)
	v_mfma_f32_32x32x16_bf16 v[52:67], v[156:159], v[4:7], v[52:67]
	v_exp_f32_e32 v106, v106
	v_exp_f32_e32 v107, v107
	ds_read_b64_tr_b16 v[4:5], v207 offset:31744
	ds_read_b64_tr_b16 v[6:7], v207 offset:32256
	s_waitcnt lgkmcnt(6)
	v_mfma_f32_32x32x16_bf16 v[68:83], v[152:155], v[10:13], v[68:83]
	v_exp_f32_e32 v108, v108
	v_exp_f32_e32 v109, v109
	s_add_u32 s98, s6, s38
	s_addc_u32 s99, s7, s39
	v_lshl_add_u64 v[254:255], v[8:9], 0, s[98:99]
	s_lshl_b32 s100, s59, 14
	s_add_i32 s100, s100, s58
	s_mov_b32 m0, s100
	s_nop 0
	global_load_lds_dwordx4 v[254:255], off
	ds_read_b64_tr_b16 v[10:11], v207 offset:32768
	ds_read_b64_tr_b16 v[12:13], v207 offset:33280
	s_waitcnt lgkmcnt(6)
	v_mfma_f32_32x32x16_bf16 v[52:67], v[152:155], v[116:119], v[52:67]
	v_exp_f32_e32 v110, v110
	v_exp_f32_e32 v111, v111
	ds_read_b64_tr_b16 v[116:117], v207 offset:36864
	ds_read_b64_tr_b16 v[118:119], v207 offset:37376
	s_waitcnt lgkmcnt(6)
	v_mfma_f32_32x32x16_bf16 v[68:83], v[148:151], v[14:17], v[68:83]
	v_exp_f32_e32 v112, v112
	v_exp_f32_e32 v113, v113
	ds_read_b64_tr_b16 v[14:15], v207 offset:33792
	ds_read_b64_tr_b16 v[16:17], v207 offset:34304
	s_waitcnt lgkmcnt(6)
	v_mfma_f32_32x32x16_bf16 v[52:67], v[148:151], v[4:7], v[52:67]
	v_exp_f32_e32 v114, v114
	v_exp_f32_e32 v115, v115
	ds_read_b64_tr_b16 v[4:5], v207 offset:37888
	ds_read_b64_tr_b16 v[6:7], v207 offset:38400
	v_lshl_add_u32 v2, s59, 13, v222
	ds_read_b128 v[192:195], v2
	ds_read_b128 v[184:187], v2 offset:512
	s_waitcnt lgkmcnt(8)
	v_mfma_f32_32x32x16_bf16 v[36:51], v[160:163], v[10:13], v[36:51]
	v_exp_f32_e32 v84, v84
	v_exp_f32_e32 v85, v85
	ds_read_b64_tr_b16 v[10:11], v207 offset:34816
	ds_read_b64_tr_b16 v[12:13], v207 offset:35328
	ds_read_b128 v[188:191], v2 offset:2048
	ds_read_b128 v[180:183], v2 offset:2560
	s_waitcnt lgkmcnt(10)
	v_mfma_f32_32x32x16_bf16 v[20:35], v[160:163], v[116:119], v[20:35]
	v_exp_f32_e32 v86, v86
	v_exp_f32_e32 v87, v87
	ds_read_b64_tr_b16 v[120:121], v207 offset:38912
	ds_read_b64_tr_b16 v[122:123], v207 offset:39424
	ds_read_b128 v[176:179], v2 offset:4096
	ds_read_b128 v[172:175], v2 offset:4608
	s_waitcnt lgkmcnt(12)
	v_mfma_f32_32x32x16_bf16 v[36:51], v[156:159], v[14:17], v[36:51]
	v_exp_f32_e32 v88, v88
	v_exp_f32_e32 v89, v89
	ds_read_b64_tr_b16 v[14:15], v207 offset:35840
	ds_read_b64_tr_b16 v[16:17], v207 offset:36352
	ds_read_b128 v[168:171], v2 offset:6144
	ds_read_b128 v[164:167], v2 offset:6656
	s_waitcnt lgkmcnt(14)
	v_mfma_f32_32x32x16_bf16 v[20:35], v[156:159], v[4:7], v[20:35]
	v_exp_f32_e32 v90, v90
	v_exp_f32_e32 v91, v91
	ds_read_b64_tr_b16 v[4:5], v207 offset:39936
	ds_read_b64_tr_b16 v[6:7], v207 offset:40448
	s_waitcnt lgkmcnt(12)
	v_mfma_f32_32x32x16_bf16 v[36:51], v[152:155], v[10:13], v[36:51]
	v_exp_f32_e32 v92, v92
	v_exp_f32_e32 v93, v93
	ds_read_b128 v[116:119], v219
	s_waitcnt lgkmcnt(9)
	v_mfma_f32_32x32x16_bf16 v[20:35], v[152:155], v[120:123], v[20:35]
	v_exp_f32_e32 v94, v94
	v_exp_f32_e32 v95, v95
	s_add_u32 s98, s6, s40
	s_addc_u32 s99, s7, s41
	v_lshl_add_u64 v[254:255], v[8:9], 0, s[98:99]
	s_lshl_b32 s100, s59, 14
	s_add_i32 s100, s100, s58
	s_addk_i32 s100, 0x2000
	s_mov_b32 m0, s100
	s_nop 0
	global_load_lds_dwordx4 v[254:255], off
	s_waitcnt lgkmcnt(5)
	v_mfma_f32_32x32x16_bf16 v[36:51], v[148:151], v[14:17], v[36:51]
	v_exp_f32_e32 v96, v96
	v_exp_f32_e32 v97, v97
	s_waitcnt lgkmcnt(1)
	v_mfma_f32_32x32x16_bf16 v[20:35], v[148:151], v[4:7], v[20:35]
	v_exp_f32_e32 v98, v98
	v_exp_f32_e32 v99, v99
	s_add_i32 s10, s59, 1
	s_cmp_lg_u32 s59, 2
	s_waitcnt vmcnt(3) lgkmcnt(0)
	s_barrier
	s_cselect_b32 s60, s10, 0
	s_add_i32 s16, s9, 2
	s_add_u32 s6, s6, 0x20000
	v_cmp_ge_u32_e32 vcc, s16, v226
	s_addc_u32 s7, s7, 0
	s_mov_b32 s11, s8
	s_cbranch_vccz .LBB0_463
	s_add_i32 s16, s9, -5
	s_branch .LBB0_467

; __global__ void __launch_bounds__(NWAVES * 64, LBW) fwd_kernel(Args A) {
	.amdhsa_kernel _Z10fwd_kernel4Args
		.amdhsa_group_segment_fixed_size 0
		.amdhsa_private_segment_fixed_size 0
		.amdhsa_kernarg_size 416
		.amdhsa_user_sgpr_count 2
		.amdhsa_user_sgpr_dispatch_ptr 0
		.amdhsa_user_sgpr_queue_ptr 0
		.amdhsa_user_sgpr_kernarg_segment_ptr 1
		.amdhsa_user_sgpr_dispatch_id 0
		.amdhsa_user_sgpr_kernarg_preload_length 0
		.amdhsa_user_sgpr_kernarg_preload_offset 0
		.amdhsa_user_sgpr_private_segment_size 0
		.amdhsa_uses_dynamic_stack 0
		.amdhsa_enable_private_segment 0
		.amdhsa_system_sgpr_workgroup_id_x 1
		.amdhsa_system_sgpr_workgroup_id_y 0
		.amdhsa_system_sgpr_workgroup_id_z 0
		.amdhsa_system_sgpr_workgroup_info 0
		.amdhsa_system_vgpr_workitem_id 0
		.amdhsa_next_free_vgpr 256
		.amdhsa_next_free_sgpr 102
		.amdhsa_accum_offset 256
		.amdhsa_reserve_vcc 1
		.amdhsa_float_round_mode_32 0
		.amdhsa_float_round_mode_16_64 0
		.amdhsa_float_denorm_mode_32 3
		.amdhsa_float_denorm_mode_16_64 3
		.amdhsa_dx10_clamp 1
		.amdhsa_ieee_mode 1
		.amdhsa_fp16_overflow 0
		.amdhsa_tg_split 0
		.amdhsa_exception_fp_ieee_invalid_op 0
		.amdhsa_exception_fp_denorm_src 0
		.amdhsa_exception_fp_ieee_div_zero 0
		.amdhsa_exception_fp_ieee_overflow 0
		.amdhsa_exception_fp_ieee_underflow 0
		.amdhsa_exception_fp_ieee_inexact 0
		.amdhsa_exception_int_div_zero 0
	.end_amdhsa_kernel

; __global__ void __launch_bounds__(NWAVES * 64, LBW) fwd_kernel(Args A) {
amdhsa.kernels:
  - .agpr_count:     0
    .args:
      - .offset:         0
        .size:           160
        .value_kind:     by_value
      - .offset:         160
        .size:           4
        .value_kind:     hidden_block_count_x
      - .offset:         164
        .size:           4
        .value_kind:     hidden_block_count_y
      - .offset:         168
        .size:           4
        .value_kind:     hidden_block_count_z
      - .offset:         172
        .size:           2
        .value_kind:     hidden_group_size_x
      - .offset:         174
        .size:           2
        .value_kind:     hidden_group_size_y
      - .offset:         176
        .size:           2
        .value_kind:     hidden_group_size_z
      - .offset:         178
        .size:           2
        .value_kind:     hidden_remainder_x
      - .offset:         180
        .size:           2
        .value_kind:     hidden_remainder_y
      - .offset:         182
        .size:           2
        .value_kind:     hidden_remainder_z
      - .offset:         200
        .size:           8
        .value_kind:     hidden_global_offset_x
      - .offset:         208
        .size:           8
        .value_kind:     hidden_global_offset_y
      - .offset:         216
        .size:           8
        .value_kind:     hidden_global_offset_z
      - .offset:         224
        .size:           2
        .value_kind:     hidden_grid_dims
      - .offset:         280
        .size:           4
        .value_kind:     hidden_dynamic_lds_size
    .group_segment_fixed_size: 0
    .kernarg_segment_align: 8
    .kernarg_segment_size: 416
    .language:       OpenCL C
    .language_version:
      - 2
      - 0
    .max_flat_workgroup_size: 512
    .name:           _Z10fwd_kernel4Args
    .private_segment_fixed_size: 0
    .sgpr_count:     108
    .sgpr_spill_count: 128
    .symbol:         _Z10fwd_kernel4Args.kd
    .uniform_work_group_size: 1
    .uses_dynamic_stack: false
    .vgpr_count:     256
    .vgpr_spill_count: 0
    .wavefront_size: 64
